# B5 + the first-arriving workgroup of each XCD starts an early non-blocking L2 write-back at arrival
# baseline (speedup 1.0000x reference)
; __device__ __forceinline__ unsigned xb_ld(unsigned* p)              { return __hip_atomic_load(p, __ATOMIC_RELAXED, __HIP_MEMORY_SCOPE_AGENT); }
; __device__ __forceinline__ unsigned xb_add(unsigned* p, unsigned v) { return __hip_atomic_fetch_add(p, v, __ATOMIC_RELAXED, __HIP_MEMORY_SCOPE_AGENT); }
; #define XB_SPIN(cond, bar) do { unsigned _sp = 0; while (cond) { __builtin_amdgcn_s_sleep(1); \
;     if ((++_sp & 255u) == 0u) { if (xb_ld(&(bar)[XB_TMO])) break; if (_sp > XB_SPIN_CAP) { atomicAdd(&(bar)[XB_TMO], 1u); break; } } } } while (0)
; __device__ __forceinline__ void xcd_barrier(const XcdBarrier& b, int tid) {
;     asm volatile("s_waitcnt vmcnt(0)" ::: "memory");
;     __syncthreads();
;     if (tid == 0) {
;         unsigned* bar = b.bar;
;         __builtin_amdgcn_s_waitcnt(0);
;         unsigned nloc = b.st[0], nx = b.st[1];
;         if (nloc == 0u) { xcd_barrier_complete(bar, b.x, nloc, nx); b.st[0] = nloc; b.st[1] = nx; }
;         const unsigned old = xb_add(&bar[XB_XSUB(b.x)], 1u);
;         const unsigned gen = old / nloc;
;         if (old + 1u == (gen + 1u) * nloc) {
;             __builtin_amdgcn_fence(__ATOMIC_RELEASE, "agent");
;             asm volatile("s_waitcnt vmcnt(0)" ::: "memory");
;             const unsigned og = xb_add(&bar[XB_TOP], 1u);
;             const unsigned tg = og / nx;
;             if (og + 1u == (tg + 1u) * nx) xb_add(&bar[XB_TOPGEN], 1u);
;             else XB_SPIN(xb_ld(&bar[XB_TOPGEN]) == tg, bar);
;             __builtin_amdgcn_fence(__ATOMIC_ACQUIRE, "agent");
;             xb_add(&bar[XB_XGEN(b.x)], 1u);
;             asm volatile("s_waitcnt vmcnt(0)" ::: "memory");
;         } else {
;             XB_SPIN(xb_ld(&bar[XB_XGEN(b.x)]) == gen, bar);
;             __builtin_amdgcn_fence(__ATOMIC_ACQUIRE, "agent");
;             asm volatile("s_waitcnt vmcnt(0)" ::: "memory");
;         }
.LBB0_62:
	s_lshl_b32 s2, s26, 8
	s_add_u32 s2, s16, s2
	s_addc_u32 s3, s17, 0
	v_mov_b32_e32 v1, 0x1000
	v_mov_b32_e32 v3, 1
	global_atomic_add v3, v1, v3, s[2:3] offset:1024 sc0
	v_cvt_f32_u32_e32 v1, v2
	v_sub_u32_e32 v4, 0, v2
	v_rcp_iflag_f32_e32 v1, v1
	s_nop 0
	v_mul_f32_e32 v1, 0x4f7ffffe, v1
	v_cvt_u32_f32_e32 v1, v1
	v_mul_lo_u32 v4, v4, v1
	v_mul_hi_u32 v4, v1, v4
	v_add_u32_e32 v1, v1, v4
	s_waitcnt vmcnt(0)
	v_mul_hi_u32 v1, v3, v1
	v_mul_lo_u32 v4, v1, v2
	v_sub_u32_e32 v4, v3, v4
	v_add_u32_e32 v5, 1, v1
	v_cmp_ge_u32_e32 vcc, v4, v2
	v_add_u32_e32 v3, 1, v3
	s_nop 0
	v_cndmask_b32_e32 v1, v1, v5, vcc
	v_sub_u32_e32 v5, v4, v2
	v_cndmask_b32_e32 v4, v4, v5, vcc
	v_add_u32_e32 v5, 1, v1
	v_cmp_ge_u32_e32 vcc, v4, v2
	s_nop 1
	v_cndmask_b32_e32 v1, v1, v5, vcc
	v_mul_lo_u32 v4, v2, v1
	v_add_u32_e32 v2, v4, v2
	v_cmp_ne_u32_e32 vcc, v3, v2
	s_and_saveexec_b64 s[4:5], vcc
	s_xor_b64 s[4:5], exec, s[4:5]
	s_cbranch_execz .LBB0_76
	v_add_u32_e32 v5, 1, v4
	v_cmp_eq_u32_e32 vcc, v5, v3
	s_cbranch_vccz .Lnofl_11
	buffer_wbl2 sc1
.Lnofl_11:
	buffer_inv sc1
	s_waitcnt lgkmcnt(0)
	v_mov_b32_e32 v0, 0x2000
	global_load_dword v0, v0, s[2:3] offset:1024 sc1
	s_add_u32 s10, s2, 0x2400
	s_addc_u32 s11, s3, 0
	s_waitcnt vmcnt(0)
	v_cmp_eq_u32_e32 vcc, v0, v1
	s_and_saveexec_b64 s[6:7], vcc
	s_cbranch_execz .LBB0_75
	s_add_u32 s8, s82, 0x4200
	s_addc_u32 s9, s83, 0
	s_mov_b32 s24, 1
	s_mov_b64 s[12:13], 0
	v_mov_b32_e32 v0, 0
	s_branch .LBB0_66

; __device__ __forceinline__ unsigned xb_ld(unsigned* p)              { return __hip_atomic_load(p, __ATOMIC_RELAXED, __HIP_MEMORY_SCOPE_AGENT); }
; __device__ __forceinline__ unsigned xb_add(unsigned* p, unsigned v) { return __hip_atomic_fetch_add(p, v, __ATOMIC_RELAXED, __HIP_MEMORY_SCOPE_AGENT); }
; #define XB_SPIN(cond, bar) do { unsigned _sp = 0; while (cond) { __builtin_amdgcn_s_sleep(1); \
;     if ((++_sp & 255u) == 0u) { if (xb_ld(&(bar)[XB_TMO])) break; if (_sp > XB_SPIN_CAP) { atomicAdd(&(bar)[XB_TMO], 1u); break; } } } } while (0)
; __device__ __forceinline__ void xcd_barrier(const XcdBarrier& b, int tid) {
;     ...
;         const unsigned old = xb_add(&bar[XB_XSUB(b.x)], 1u);
;         const unsigned gen = old / nloc;
;         if (old + 1u == (gen + 1u) * nloc) {
;             __builtin_amdgcn_fence(__ATOMIC_RELEASE, "agent");
;             asm volatile("s_waitcnt vmcnt(0)" ::: "memory");
;             const unsigned og = xb_add(&bar[XB_TOP], 1u);
;             const unsigned tg = og / nx;
;             if (og + 1u == (tg + 1u) * nx) xb_add(&bar[XB_TOPGEN], 1u);
;             else XB_SPIN(xb_ld(&bar[XB_TOPGEN]) == tg, bar);
;             __builtin_amdgcn_fence(__ATOMIC_ACQUIRE, "agent");
;             xb_add(&bar[XB_XGEN(b.x)], 1u);
;             asm volatile("s_waitcnt vmcnt(0)" ::: "memory");
;         } else {
;             XB_SPIN(xb_ld(&bar[XB_XGEN(b.x)]) == gen, bar);
.LBB0_176:
	v_readlane_b32 s2, v254, 7
	v_readlane_b32 s3, v254, 8
	v_cvt_f32_u32_e32 v1, v2
	v_sub_u32_e32 v4, 0, v2
	v_rcp_iflag_f32_e32 v1, v1
	s_nop 1
	global_atomic_add v3, v161, v239, s[2:3] sc0
	v_mul_f32_e32 v1, 0x4f7ffffe, v1
	v_cvt_u32_f32_e32 v1, v1
	v_mul_lo_u32 v4, v4, v1
	v_mul_hi_u32 v4, v1, v4
	v_add_u32_e32 v1, v1, v4
	s_waitcnt vmcnt(0)
	v_mul_hi_u32 v1, v3, v1
	v_mul_lo_u32 v4, v1, v2
	v_sub_u32_e32 v4, v3, v4
	v_add_u32_e32 v5, 1, v1
	v_cmp_ge_u32_e32 vcc, v4, v2
	v_add_u32_e32 v3, 1, v3
	s_nop 0
	v_cndmask_b32_e32 v1, v1, v5, vcc
	v_sub_u32_e32 v5, v4, v2
	v_cndmask_b32_e32 v4, v4, v5, vcc
	v_add_u32_e32 v5, 1, v1
	v_cmp_ge_u32_e32 vcc, v4, v2
	s_nop 1
	v_cndmask_b32_e32 v1, v1, v5, vcc
	v_mul_lo_u32 v4, v2, v1
	v_add_u32_e32 v2, v4, v2
	v_cmp_ne_u32_e32 vcc, v3, v2
	s_and_saveexec_b64 s[2:3], vcc
	s_xor_b64 s[2:3], exec, s[2:3]
	s_cbranch_execz .LBB0_190
	v_add_u32_e32 v5, 1, v4
	v_cmp_eq_u32_e32 vcc, v5, v3
	s_cbranch_vccz .Lnofl_10
	buffer_wbl2 sc1
.Lnofl_10:
	buffer_inv sc1
	v_readlane_b32 s4, v254, 9
	v_readlane_b32 s5, v254, 10
	s_waitcnt lgkmcnt(0)
	s_nop 3
	global_load_dword v0, v161, s[4:5] sc1
	s_waitcnt vmcnt(0)
	v_cmp_eq_u32_e32 vcc, v0, v1
	s_and_saveexec_b64 s[4:5], vcc
	s_cbranch_execz .LBB0_189
	s_mov_b32 s18, 1
	s_mov_b64 s[6:7], 0
	s_branch .LBB0_180

; __device__ __forceinline__ unsigned xb_ld(unsigned* p)              { return __hip_atomic_load(p, __ATOMIC_RELAXED, __HIP_MEMORY_SCOPE_AGENT); }
; __device__ __forceinline__ unsigned xb_add(unsigned* p, unsigned v) { return __hip_atomic_fetch_add(p, v, __ATOMIC_RELAXED, __HIP_MEMORY_SCOPE_AGENT); }
; #define XB_SPIN(cond, bar) do { unsigned _sp = 0; while (cond) { __builtin_amdgcn_s_sleep(1); \
;     if ((++_sp & 255u) == 0u) { if (xb_ld(&(bar)[XB_TMO])) break; if (_sp > XB_SPIN_CAP) { atomicAdd(&(bar)[XB_TMO], 1u); break; } } } } while (0)
; __device__ __forceinline__ void xcd_barrier(const XcdBarrier& b, int tid) {
;     ...
;         const unsigned old = xb_add(&bar[XB_XSUB(b.x)], 1u);
;         const unsigned gen = old / nloc;
;         if (old + 1u == (gen + 1u) * nloc) {
;             __builtin_amdgcn_fence(__ATOMIC_RELEASE, "agent");
;             asm volatile("s_waitcnt vmcnt(0)" ::: "memory");
;             const unsigned og = xb_add(&bar[XB_TOP], 1u);
;             const unsigned tg = og / nx;
;             if (og + 1u == (tg + 1u) * nx) xb_add(&bar[XB_TOPGEN], 1u);
;             else XB_SPIN(xb_ld(&bar[XB_TOPGEN]) == tg, bar);
;             __builtin_amdgcn_fence(__ATOMIC_ACQUIRE, "agent");
;             xb_add(&bar[XB_XGEN(b.x)], 1u);
;             asm volatile("s_waitcnt vmcnt(0)" ::: "memory");
;         } else {
;             XB_SPIN(xb_ld(&bar[XB_XGEN(b.x)]) == gen, bar);
.LBB0_1502:
	v_readlane_b32 s0, v254, 7
	v_readlane_b32 s1, v254, 8
	v_cvt_f32_u32_e32 v1, v2
	v_sub_u32_e32 v4, 0, v2
	v_rcp_iflag_f32_e32 v1, v1
	s_nop 1
	global_atomic_add v3, v161, v239, s[0:1] sc0
	v_mul_f32_e32 v1, 0x4f7ffffe, v1
	v_cvt_u32_f32_e32 v1, v1
	v_mul_lo_u32 v4, v4, v1
	v_mul_hi_u32 v4, v1, v4
	v_add_u32_e32 v1, v1, v4
	s_waitcnt vmcnt(0)
	v_mul_hi_u32 v1, v3, v1
	v_mul_lo_u32 v4, v1, v2
	v_sub_u32_e32 v4, v3, v4
	v_add_u32_e32 v5, 1, v1
	v_cmp_ge_u32_e32 vcc, v4, v2
	v_add_u32_e32 v3, 1, v3
	s_nop 0
	v_cndmask_b32_e32 v1, v1, v5, vcc
	v_sub_u32_e32 v5, v4, v2
	v_cndmask_b32_e32 v4, v4, v5, vcc
	v_add_u32_e32 v5, 1, v1
	v_cmp_ge_u32_e32 vcc, v4, v2
	s_nop 1
	v_cndmask_b32_e32 v1, v1, v5, vcc
	v_mul_lo_u32 v4, v2, v1
	v_add_u32_e32 v2, v4, v2
	v_cmp_ne_u32_e32 vcc, v3, v2
	s_and_saveexec_b64 s[0:1], vcc
	s_xor_b64 s[4:5], exec, s[0:1]
	s_cbranch_execz .LBB0_1516
	v_add_u32_e32 v5, 1, v4
	v_cmp_eq_u32_e32 vcc, v5, v3
	s_cbranch_vccz .Lnofl_2
	buffer_wbl2 sc1
.Lnofl_2:
	buffer_inv sc1
	v_readlane_b32 s0, v254, 9
	v_readlane_b32 s1, v254, 10
	s_waitcnt lgkmcnt(0)
	s_nop 3
	global_load_dword v0, v161, s[0:1] sc1
	s_waitcnt vmcnt(0)
	v_cmp_eq_u32_e32 vcc, v0, v1
	s_and_saveexec_b64 s[6:7], vcc
	s_cbranch_execz .LBB0_1515
	s_mov_b32 s0, 1
	s_mov_b64 s[8:9], 0
	s_branch .LBB0_1506

; __device__ __forceinline__ unsigned xb_ld(unsigned* p)              { return __hip_atomic_load(p, __ATOMIC_RELAXED, __HIP_MEMORY_SCOPE_AGENT); }
; __device__ __forceinline__ unsigned xb_add(unsigned* p, unsigned v) { return __hip_atomic_fetch_add(p, v, __ATOMIC_RELAXED, __HIP_MEMORY_SCOPE_AGENT); }
; #define XB_SPIN(cond, bar) do { unsigned _sp = 0; while (cond) { __builtin_amdgcn_s_sleep(1); \
;     if ((++_sp & 255u) == 0u) { if (xb_ld(&(bar)[XB_TMO])) break; if (_sp > XB_SPIN_CAP) { atomicAdd(&(bar)[XB_TMO], 1u); break; } } } } while (0)
; __device__ __forceinline__ void xcd_barrier(const XcdBarrier& b, int tid) {
;     ...
;         const unsigned old = xb_add(&bar[XB_XSUB(b.x)], 1u);
;         const unsigned gen = old / nloc;
;         if (old + 1u == (gen + 1u) * nloc) {
;             __builtin_amdgcn_fence(__ATOMIC_RELEASE, "agent");
;             asm volatile("s_waitcnt vmcnt(0)" ::: "memory");
;             const unsigned og = xb_add(&bar[XB_TOP], 1u);
;             const unsigned tg = og / nx;
;             if (og + 1u == (tg + 1u) * nx) xb_add(&bar[XB_TOPGEN], 1u);
;             else XB_SPIN(xb_ld(&bar[XB_TOPGEN]) == tg, bar);
;             __builtin_amdgcn_fence(__ATOMIC_ACQUIRE, "agent");
;             xb_add(&bar[XB_XGEN(b.x)], 1u);
;             asm volatile("s_waitcnt vmcnt(0)" ::: "memory");
;         } else {
;             XB_SPIN(xb_ld(&bar[XB_XGEN(b.x)]) == gen, bar);
.LBB0_1826:
	v_readlane_b32 s2, v254, 7
	v_mov_b32_e32 v3, 0
	v_mov_b32_e32 v1, 1
	v_readlane_b32 s3, v254, 8
	v_sub_u32_e32 v5, 0, v2
	s_nop 3
	global_atomic_add v4, v3, v1, s[2:3] sc0
	v_cvt_f32_u32_e32 v1, v2
	v_rcp_iflag_f32_e32 v1, v1
	s_nop 0
	v_mul_f32_e32 v1, 0x4f7ffffe, v1
	v_cvt_u32_f32_e32 v1, v1
	v_mul_lo_u32 v5, v5, v1
	v_mul_hi_u32 v5, v1, v5
	v_add_u32_e32 v1, v1, v5
	s_waitcnt vmcnt(0)
	v_mul_hi_u32 v1, v4, v1
	v_mul_lo_u32 v5, v1, v2
	v_sub_u32_e32 v5, v4, v5
	v_add_u32_e32 v6, 1, v1
	v_cmp_ge_u32_e32 vcc, v5, v2
	v_add_u32_e32 v4, 1, v4
	s_nop 0
	v_cndmask_b32_e32 v1, v1, v6, vcc
	v_sub_u32_e32 v6, v5, v2
	v_cndmask_b32_e32 v5, v5, v6, vcc
	v_add_u32_e32 v6, 1, v1
	v_cmp_ge_u32_e32 vcc, v5, v2
	s_nop 1
	v_cndmask_b32_e32 v1, v1, v6, vcc
	v_mul_lo_u32 v5, v2, v1
	v_add_u32_e32 v2, v5, v2
	v_cmp_ne_u32_e32 vcc, v4, v2
	s_and_saveexec_b64 s[2:3], vcc
	s_xor_b64 s[2:3], exec, s[2:3]
	s_cbranch_execz .LBB0_1840
	v_add_u32_e32 v6, 1, v5
	v_cmp_eq_u32_e32 vcc, v6, v4
	s_cbranch_vccz .Lnofl_0
	buffer_wbl2 sc1
.Lnofl_0:
	buffer_inv sc1
	v_readlane_b32 s4, v254, 9
	v_readlane_b32 s5, v254, 10
	s_waitcnt lgkmcnt(0)
	s_nop 3
	global_load_dword v0, v3, s[4:5] sc1
	s_waitcnt vmcnt(0)
	v_cmp_eq_u32_e32 vcc, v0, v1
	s_and_saveexec_b64 s[4:5], vcc
	s_cbranch_execz .LBB0_1839
	s_mov_b32 s16, 1
	s_mov_b64 s[6:7], 0
	v_mov_b32_e32 v0, 0
	s_branch .LBB0_1830
